# P2: first work item of workgroup c is item c (no contended atomic fetch at P2 start); queue counter pre-bumped at kernel start
# baseline (speedup 1.0000x reference)
_Z9hymba_fwd4Args:
	s_load_dwordx2 s[52:53], s[0:1], 0x90
	s_load_dwordx4 s[28:31], s[0:1], 0x80
	s_add_u32 s6, s0, 0x98
	v_and_b32_e32 v254, 0x3ff, v0
	s_addc_u32 s7, s1, 0
	v_readfirstlane_b32 s56, v254
	v_cmp_gt_u32_e32 vcc, 32, v254
	s_and_saveexec_b64 s[4:5], vcc
	v_lshl_add_u32 v1, v254, 2, 0
	v_add_u32_e32 v1, 0x20000, v1
	v_mov_b32_e32 v2, 0
	ds_write_b32 v1, v2
	s_or_b64 exec, exec, s[4:5]
	s_load_dwordx2 s[10:11], s[0:1], 0x98
	s_load_dword s33, s[0:1], 0xa0
	s_waitcnt lgkmcnt(0)
	s_barrier
	s_add_u32 s54, s52, 0x1000
	s_getreg_b32 s3, hwreg(HW_REG_XCC_ID, 0, 4)
	s_addc_u32 s55, s53, 0
	s_and_b32 s3, s3, 15
	v_cmp_eq_u32_e64 s[92:93], 0, v254
	s_and_saveexec_b64 s[4:5], s[92:93]
	s_cbranch_execz .LBB0_5
	s_mov_b64 s[12:13], exec
	v_mbcnt_lo_u32_b32 v1, s12, 0
	v_mbcnt_hi_u32_b32 v1, s13, v1
	v_cmp_eq_u32_e32 vcc, 0, v1
	s_and_b64 s[14:15], exec, vcc
	s_mov_b64 exec, s[14:15]
	s_cbranch_execz .LBB0_5
	s_lshl_b32 s14, s3, 8
	s_bcnt1_i32_b64 s12, s[12:13]
	v_mov_b32_e32 v1, s14
	v_mov_b32_e32 v2, s12
	global_atomic_add v1, v2, s[54:55] offset:1024
	s_and_b32 s12, s2, 7
	s_lshl_b32 s12, s12, 3
	s_bfe_u32 s13, s2, 0x30003
	s_add_i32 s12, s12, s13
	s_lshl_b32 s12, s12, 6
	s_add_i32 s12, s12, 0x4000
	s_lshl_b32 s14, 1, s3
	v_mov_b32_e32 v1, s12
	v_mov_b32_e32 v2, s14
	global_atomic_or v1, v2, s[54:55]
	v_mov_b32_e32 v1, 0
	v_mov_b32_e32 v2, 1
	global_atomic_add v1, v2, s[52:53]

.LBB0_243:
	s_or_b64 exec, exec, s[0:1]
	s_waitcnt lgkmcnt(0)
	v_mov_b32_e32 v0, v254
	s_barrier
	s_and_b32 s4, s2, 7
	s_lshl_b32 s4, s4, 3
	s_bfe_u32 s5, s2, 0x30003
	s_add_i32 s4, s4, s5
	s_lshl_b32 s4, s4, 6
	s_add_i32 s4, s4, 0x5000
	v_mov_b32_e32 v252, s4
	global_load_dword v253, v252, s[52:53] sc1
	s_mov_b32 s0, 0x46800000
	v_and_b32_e32 v1, 63, v0
	v_lshlrev_b32_e32 v1, 2, v1
	global_load_dword v2, v1, s[24:25]
	global_load_dword v3, v1, s[26:27]
	global_load_dword v4, v1, s[36:37]
	global_load_dword v5, v1, s[38:39]
	global_load_dword v6, v1, s[20:21]
	global_load_dword v7, v1, s[22:23]
	v_mbcnt_lo_u32_b32 v1, -1, 0
	v_mbcnt_hi_u32_b32 v1, -1, v1
	v_and_b32_e32 v8, 64, v1
	v_xor_b32_e32 v9, 1, v1
	v_add_u32_e32 v8, 64, v8
	v_xor_b32_e32 v10, 2, v1
	v_cmp_lt_i32_e32 vcc, v9, v8
	v_xor_b32_e32 v11, 4, v1
	v_xor_b32_e32 v12, 8, v1
	v_cndmask_b32_e32 v9, v1, v9, vcc
	v_cmp_lt_i32_e32 vcc, v10, v8
	v_xor_b32_e32 v13, 16, v1
	v_xor_b32_e32 v14, 32, v1
	v_cndmask_b32_e32 v10, v1, v10, vcc
	v_cmp_lt_i32_e32 vcc, v11, v8
	s_add_u32 s38, s52, 0x3800000
	s_addc_u32 s44, s53, 0
	v_cndmask_b32_e32 v11, v1, v11, vcc
	v_cmp_lt_i32_e32 vcc, v12, v8
	s_add_u32 s45, s52, 0x4800000
	s_addc_u32 s46, s53, 0
	v_cndmask_b32_e32 v12, v1, v12, vcc
	v_cmp_lt_i32_e32 vcc, v13, v8
	s_add_u32 s47, s52, 0x5800000
	s_addc_u32 s48, s53, 0
	v_cndmask_b32_e32 v13, v1, v13, vcc
	v_cmp_lt_i32_e32 vcc, v14, v8
	v_lshlrev_b32_e32 v8, 2, v9
	v_lshlrev_b32_e32 v9, 2, v10
	v_cndmask_b32_e32 v1, v1, v14, vcc
	v_lshlrev_b32_e32 v10, 2, v11
	v_lshlrev_b32_e32 v11, 2, v12
	v_lshlrev_b32_e32 v193, 2, v13
	v_lshlrev_b32_e32 v194, 2, v1
	s_add_u32 s49, s52, 0x6800000
	s_addc_u32 s50, s53, 0
	s_add_u32 s51, s52, 0x7800000
	s_addc_u32 s56, s53, 0
	s_add_u32 s57, s52, 0x8800000
	s_addc_u32 s58, s53, 0
	s_add_u32 s16, s52, 0xb800000
	s_mov_b32 s21, 0
	s_mov_b32 s39, 0x3fb8aa3b
	s_addc_u32 s17, s53, 0
	v_mov_b32_e32 v131, 0
	s_add_i32 s63, 0, 0x20040
	s_movk_i32 s64, 0x70
	v_mov_b32_e32 v195, 0x358637bd
	s_mov_b32 s65, 0x800000
	s_movk_i32 s66, 0xffef
	s_movk_i32 s67, 0xffe7
	v_mov_b32_e32 v196, 0x3f80
	v_mov_b32_e32 v197, 0x3f803f80
	v_mov_b32_e32 v198, 0x42800000
	v_mov_b32_e32 v199, 0xc6ea6000
	s_waitcnt vmcnt(4)
	v_mul_f32_e32 v1, v2, v3
	ds_bpermute_b32 v1, v8, v1
	s_waitcnt vmcnt(2)
	v_mul_f32_e32 v12, v4, v5
	s_waitcnt vmcnt(1)
	v_and_b32_e32 v13, 0x7fffffff, v6
	s_waitcnt vmcnt(0)
	v_and_b32_e32 v14, 0x7fffffff, v7
	ds_bpermute_b32 v12, v8, v12
	ds_bpermute_b32 v13, v8, v13
	ds_bpermute_b32 v8, v8, v14
	v_max_f32_e64 v6, |v6|, |v6|
	s_waitcnt lgkmcnt(3)
	v_fmac_f32_e32 v1, v2, v3
	s_waitcnt lgkmcnt(2)
	v_fmac_f32_e32 v12, v4, v5
	s_waitcnt lgkmcnt(1)
	v_max_f32_e32 v2, v13, v13
	v_max_f32_e64 v7, |v7|, |v7|
	s_waitcnt lgkmcnt(0)
	v_max_f32_e32 v3, v8, v8
	ds_bpermute_b32 v4, v9, v1
	ds_bpermute_b32 v5, v9, v12
	v_max_f32_e32 v2, v6, v2
	v_max_f32_e32 v3, v7, v3
	ds_bpermute_b32 v6, v9, v2
	ds_bpermute_b32 v7, v9, v3
	s_waitcnt lgkmcnt(3)
	v_add_f32_e32 v1, v1, v4
	s_waitcnt lgkmcnt(2)
	v_add_f32_e32 v4, v12, v5
	ds_bpermute_b32 v5, v10, v1
	ds_bpermute_b32 v8, v10, v4
	s_waitcnt lgkmcnt(3)
	v_max_f32_e32 v6, v6, v6
	s_waitcnt lgkmcnt(2)
	v_max_f32_e32 v7, v7, v7
	v_max_f32_e32 v2, v2, v6
	v_max_f32_e32 v3, v3, v7
	ds_bpermute_b32 v6, v10, v2
	ds_bpermute_b32 v7, v10, v3
	s_waitcnt lgkmcnt(3)
	v_add_f32_e32 v1, v1, v5
	s_waitcnt lgkmcnt(2)
	v_add_f32_e32 v4, v4, v8
	ds_bpermute_b32 v5, v11, v1
	ds_bpermute_b32 v8, v11, v4
	s_waitcnt lgkmcnt(3)
	v_max_f32_e32 v6, v6, v6
	s_waitcnt lgkmcnt(2)
	v_max_f32_e32 v7, v7, v7
	v_max_f32_e32 v2, v2, v6
	v_max_f32_e32 v3, v3, v7
	ds_bpermute_b32 v6, v11, v2
	ds_bpermute_b32 v7, v11, v3
	s_waitcnt lgkmcnt(3)
	v_add_f32_e32 v1, v1, v5
	s_waitcnt lgkmcnt(2)
	v_add_f32_e32 v4, v4, v8
	ds_bpermute_b32 v5, v193, v1
	ds_bpermute_b32 v8, v193, v4
	s_waitcnt lgkmcnt(3)
	v_max_f32_e32 v6, v6, v6
	s_waitcnt lgkmcnt(2)
	v_max_f32_e32 v7, v7, v7
	v_max_f32_e32 v2, v2, v6
	v_max_f32_e32 v3, v3, v7
	ds_bpermute_b32 v6, v193, v2
	ds_bpermute_b32 v7, v193, v3
	s_waitcnt lgkmcnt(3)
	v_add_f32_e32 v1, v1, v5
	s_waitcnt lgkmcnt(2)
	v_add_f32_e32 v4, v4, v8
	ds_bpermute_b32 v5, v194, v1
	ds_bpermute_b32 v8, v194, v4
	s_waitcnt lgkmcnt(3)
	v_max_f32_e32 v6, v6, v6
	s_waitcnt lgkmcnt(2)
	v_max_f32_e32 v7, v7, v7
	v_max_f32_e32 v2, v2, v6
	v_max_f32_e32 v3, v3, v7
	s_waitcnt lgkmcnt(1)
	v_add_f32_e32 v1, v1, v5
	s_waitcnt lgkmcnt(0)
	v_add_f32_e32 v4, v4, v8
	ds_bpermute_b32 v5, v194, v2
	ds_bpermute_b32 v6, v194, v3
	v_mul_f32_e32 v1, 0x3fb8aa3b, v1
	v_mul_f32_e32 v4, 0x3fb8aa3b, v4
	v_exp_f32_e32 v1, v1
	v_exp_f32_e32 v4, v4
	s_waitcnt lgkmcnt(1)
	v_max_f32_e32 v5, v5, v5
	s_waitcnt lgkmcnt(0)
	v_max_f32_e32 v6, v6, v6
	v_max_f32_e32 v2, v2, v5
	v_sub_f32_e32 v1, v1, v4
	v_max_f32_e32 v3, v3, v6
	v_add_f32_e32 v180, 0x3e4ccccd, v1
	v_mul_f32_e32 v1, 0x41000000, v2
	v_mul_f32_e32 v1, v1, v3
	v_mul_f32_e32 v1, 0x3f828f5c, v1
	v_mov_b32_e32 v2, 0x41c80000
	v_fmac_f32_e32 v2, 2.0, v1
	v_mul_f32_e32 v1, 4.0, v2
	v_ceil_f32_e32 v1, v1
	v_mov_b32_e32 v3, 0x46800000
	v_cmp_nle_f32_e32 vcc, s0, v1
	v_mov_b32_e32 v181, v180
	s_nop 0
	v_cndmask_b32_e32 v1, v3, v1, vcc
	s_nop 0
	v_readfirstlane_b32 s59, v1
	v_mul_f32_e32 v1, 0x41800000, v2
	v_ceil_f32_e32 v1, v1
	v_cmp_nle_f32_e32 vcc, s0, v1
	s_nop 1
	v_cndmask_b32_e32 v1, v3, v1, vcc
	s_nop 0
	v_readfirstlane_b32 s60, v1
	v_mul_f32_e32 v1, 0x42800000, v2
	v_ceil_f32_e32 v1, v1
	v_cmp_nle_f32_e32 vcc, s0, v1
	s_nop 1
	v_cndmask_b32_e32 v1, v3, v1, vcc
	s_nop 0
	v_readfirstlane_b32 s61, v1
	v_mul_f32_e32 v1, 0x43800000, v2
	v_ceil_f32_e32 v1, v1
	v_cmp_nle_f32_e32 vcc, s0, v1
	v_cmp_eq_u32_e64 s[0:1], 0, v0
	s_nop 0
	v_cndmask_b32_e32 v1, v3, v1, vcc
	s_nop 0
	v_readfirstlane_b32 s62, v1
	s_mov_b32 s68, s2
	s_mov_b64 s[4:5], -1
	s_branch .Lq_first

.Lq_first:
	s_cmpk_gt_i32 s68, 0x2ff
	s_cbranch_scc1 .LBB0_245
	s_cmpk_gt_i32 s68, 0xff
	s_cbranch_scc0 .LBB0_296
	s_add_i32 s20, s68, 0xffffff00
	s_cmpk_gt_u32 s68, 0x1ff
	s_cbranch_scc0 .LBB0_268
	v_mov_b32_e32 v32, v254
	s_and_b32 s8, s68, 63
	v_readfirstlane_b32 s36, v32
	s_ashr_i32 s6, s36, 6
	s_and_b32 s69, s6, 3
	s_lshr_b32 s76, s20, 7
	s_lshl_b32 s5, s8, 7
	s_lshl_b32 s4, s69, 5
	s_ashr_i32 s37, s36, 8
	s_sub_i32 s26, 3, s76
	s_bfe_u32 s7, s68, 0x10006
	s_or_b32 s4, s4, s5
	s_cmp_eq_u32 s76, 3
	v_mov_b32_e32 v0, s60
	v_mov_b32_e32 v1, s59
	s_cselect_b64 vcc, -1, 0
	v_cndmask_b32_e32 v0, v0, v1, vcc
	v_cvt_i32_f32_e32 v0, v0
	v_and_or_b32 v159, v32, 31, s4
	v_bfe_u32 v34, v32, 4, 2
	v_bfe_u32 v33, v32, 5, 1
	v_readfirstlane_b32 s4, v0
	s_sub_i32 s9, s5, s4
	s_sub_i32 s22, s9, 63
	s_ashr_i32 s9, s9, 6
	s_cmp_gt_i32 s22, 0
	s_cselect_b32 s72, s9, 0
	s_add_i32 s4, s4, s5
	s_addk_i32 s4, 0x7f
	s_ashr_i32 s9, s4, 6
	s_lshl_b32 s71, s8, 1
	s_or_b32 s4, s71, 1
	s_min_i32 s9, s9, 0x7f
	s_sub_i32 s22, s71, s72
	s_sub_i32 s9, s9, s4
	s_add_i32 s70, s22, s9
	s_lshl_b32 s9, s7, 3
	s_lshl_b32 s22, s26, 1
	s_or_b32 s9, s22, s9
	s_lshl_b32 s22, s9, 20
	s_add_u32 s22, s45, s22
	s_addc_u32 s23, s46, 0
	v_bfe_u32 v0, v32, 3, 3
	s_add_u32 s24, s22, 0x100000
	v_lshl_or_b32 v2, s6, 3, v0
	s_addc_u32 s25, s23, 0
	s_lshl_b32 s27, s7, 23
	s_lshl_b32 s7, s26, 21
	s_lshl_b32 s29, s6, 10
	s_add_i32 s6, s37, s9
	s_or_b32 s28, s7, s27
	s_ashr_i32 s7, s6, 31
	v_lshrrev_b32_e32 v0, 1, v2
	s_lshl_b64 s[6:7], s[6:7], 20
	v_xor_b32_e32 v0, v0, v32
	s_add_u32 s6, s38, s6
	v_lshlrev_b32_e32 v3, 4, v0
	v_and_b32_e32 v36, 15, v32
	v_lshlrev_b32_e32 v0, 2, v34
	s_addc_u32 s7, s44, s7
	v_lshlrev_b32_e32 v130, 7, v159
	v_bitop3_b32 v5, v0, v36, s69 bitop3:0x36
	v_lshl_add_u64 v[0:1], s[6:7], 0, v[130:131]
	v_lshlrev_b32_e32 v156, 4, v33
	v_mov_b32_e32 v157, v131
	v_lshl_add_u64 v[0:1], v[0:1], 0, v[156:157]
	s_waitcnt vmcnt(0)
	global_load_dwordx4 v[144:147], v[0:1], off
	global_load_dwordx4 v[140:143], v[0:1], off offset:32
	global_load_dwordx4 v[136:139], v[0:1], off offset:64
	global_load_dwordx4 v[132:135], v[0:1], off offset:96
	v_lshlrev_b32_e32 v1, 1, v32
	v_lshrrev_b32_e32 v37, 1, v32
	v_and_b32_e32 v0, 19, v32
	v_and_b32_e32 v1, 8, v1
	v_and_b32_e32 v6, 4, v37
	v_or3_b32 v35, v6, v0, v1
	v_lshlrev_b32_e32 v0, 7, v2
	s_add_u32 s6, s47, s28
	s_addc_u32 s7, s48, 0
	s_lshl_b32 s9, s37, 13
	v_and_or_b32 v185, v3, s64, v0
	v_lshl_or_b32 v4, v34, 8, s29
	v_lshl_or_b32 v0, v35, 7, s9
	v_lshl_add_u32 v1, s8, 14, v185
	s_add_i32 s75, s29, 0
	s_mov_b32 s9, m0
	s_mov_b32 m0, s75
	s_nop 0
	global_load_lds_dwordx4 v1, s[22:23]
	s_mov_b32 m0, s9
	v_lshl_or_b32 v170, v5, 4, v4
	s_add_i32 s77, s75, 0x2000
	s_mov_b32 s9, m0
	s_mov_b32 m0, s77
	s_nop 0
	global_load_lds_dwordx4 v1, s[24:25]
	s_mov_b32 m0, s9
	s_lshl_b32 s8, s8, 15
	v_lshrrev_b32_e32 v8, 1, v35
	v_add_u32_e32 v169, 0x2000, v170
	v_add_u32_e32 v1, s8, v170
	s_add_i32 s73, s75, 0x4000
	s_mov_b32 s9, m0
	s_mov_b32 m0, s73
	s_nop 0
	global_load_lds_dwordx4 v1, s[6:7]
	s_mov_b32 m0, s9
	v_add_u32_e32 v1, s8, v169
	s_add_i32 s74, s75, 0x6000
	s_mov_b32 s8, m0
	s_mov_b32 m0, s74
	s_nop 0
	global_load_lds_dwordx4 v1, s[6:7]
	s_mov_b32 m0, s8
	v_add_u32_e32 v9, 0, v0
	v_bitop3_b32 v0, v8, v33, 7 bitop3:0x6c
	v_lshl_add_u32 v1, s4, 13, v185
	s_add_i32 s78, s75, 0x8000
	s_mov_b32 s8, m0
	s_mov_b32 m0, s78
	s_nop 0
	global_load_lds_dwordx4 v1, s[22:23]
	s_mov_b32 m0, s8
	v_lshlrev_b32_e32 v0, 4, v0
	s_add_i32 s79, s75, 0xa000
	s_mov_b32 s8, m0
	s_mov_b32 m0, s79
	s_nop 0
	global_load_lds_dwordx4 v1, s[24:25]
	s_mov_b32 m0, s8
	v_add_u32_e32 v171, v9, v0
	s_waitcnt vmcnt(0) lgkmcnt(0)
	s_barrier
	ds_read_b128 v[0:3], v171
	ds_read_b128 v[4:7], v171 offset:4096
	s_waitcnt lgkmcnt(1)
	v_mfma_f32_32x32x16_bf16 v[16:31], v[0:3], v[144:147], 0
	v_or_b32_e32 v0, 2, v33
	v_bitop3_b32 v0, v8, v0, 7 bitop3:0x6c
	v_lshlrev_b32_e32 v0, 4, v0
	v_add_u32_e32 v174, v9, v0
	ds_read_b128 v[0:3], v174
	ds_read_b128 v[38:41], v174 offset:4096
	s_add_i32 s70, s70, 2
	s_cmp_lt_i32 s70, 3
	s_waitcnt lgkmcnt(1)
	v_mfma_f32_32x32x16_bf16 v[16:31], v[0:3], v[140:143], v[16:31]
	v_or_b32_e32 v0, 4, v33
	v_bitop3_b32 v0, v8, v0, 7 bitop3:0x6c
	v_lshlrev_b32_e32 v0, 4, v0
	v_add_u32_e32 v172, v9, v0
	ds_read_b128 v[0:3], v172
	ds_read_b128 v[42:45], v172 offset:4096
	s_waitcnt lgkmcnt(1)
	v_mfma_f32_32x32x16_bf16 v[16:31], v[0:3], v[136:139], v[16:31]
	v_or_b32_e32 v0, 6, v33
	v_bitop3_b32 v0, v8, v0, 7 bitop3:0x6c
	v_lshlrev_b32_e32 v0, 4, v0
	v_add_u32_e32 v173, v9, v0
	ds_read_b128 v[0:3], v173
	ds_read_b128 v[46:49], v173 offset:4096
	s_waitcnt lgkmcnt(0)
	s_barrier
	s_waitcnt lgkmcnt(1)
	v_mfma_f32_32x32x16_bf16 v[16:31], v[0:3], v[132:135], v[16:31]
	v_mfma_f32_32x32x16_bf16 v[0:15], v[4:7], v[144:147], 0
	v_mfma_f32_32x32x16_bf16 v[0:15], v[38:41], v[140:143], v[0:15]
	v_mfma_f32_32x32x16_bf16 v[0:15], v[42:45], v[136:139], v[0:15]
	s_waitcnt lgkmcnt(0)
	v_mfma_f32_32x32x16_bf16 v[0:15], v[46:49], v[132:135], v[0:15]
	s_cbranch_scc1 .LBB0_255
	s_lshl_b32 s8, s72, 13
	s_add_i32 s9, s8, 0x4000
	s_cmp_lt_i32 s72, s71
	s_cselect_b32 s8, s8, s9
	v_add_u32_e32 v38, s8, v185
	s_mov_b32 s8, m0
	s_mov_b32 m0, s75
	s_nop 0
	global_load_lds_dwordx4 v38, s[22:23]
	s_mov_b32 m0, s8
	s_nop 0
	s_mov_b32 s8, m0
	s_mov_b32 m0, s77
	s_nop 0
	global_load_lds_dwordx4 v38, s[24:25]
	s_mov_b32 m0, s8
